# QK accumulator init variant without raised wave priority in the attention phase
# baseline (speedup 1.0000x reference)
.LBB0_1297:
.LBB0_1298:
	s_cmp_lt_i32 s14, 7
	s_cselect_b64 s[0:1], -1, 0
	s_cmp_gt_i32 s15, 6
	s_cselect_b64 s[4:5], -1, 0
	s_and_b64 s[0:1], s[0:1], s[4:5]
	s_andn2_b64 vcc, exec, s[0:1]
	s_cbranch_vccnz .LBB0_1473
	v_readfirstlane_b32 s62, v0
	s_nop 3
	s_lshr_b32 s62, s62, 8
	s_cmp_eq_u32 s62, 1
	s_cbranch_scc0 .Lp6_noprio
	s_setprio 0
